# nt hint on the attention K/V LDS-DMA and on the conv streaming loads so the phase outputs stay in the XCD L2
# speedup vs baseline: 1.0041x; 1.0041x over previous
.LBB0_452:
	s_lshl_b32 s20, s71, 7
	s_and_b32 s16, s20, 0x780
	s_sub_i32 s21, 29, s16
	s_mov_b64 s[16:17], 0
	v_mov_b32_e32 v112, v204
	v_mov_b32_e32 v113, v189
	v_mov_b32_e32 v114, v203
	s_waitcnt vmcnt(0)
	s_barrier
	v_add_u32_e32 v122, s38, v113
	v_ashrrev_i32_e32 v123, 31, v122
	v_lshlrev_b64 v[120:121], 11, v[122:123]
	v_lshl_add_u64 v[120:121], v[110:111], 0, v[120:121]
	s_mov_b32 s18, 0x2000
	s_mov_b32 s19, 0
	v_mov_b64_e32 v[0:1], 0
	v_mov_b64_e32 v[2:3], 0
	v_mov_b64_e32 v[4:5], 0
	v_mov_b64_e32 v[6:7], 0
	v_mov_b64_e32 v[8:9], 0
	v_mov_b64_e32 v[10:11], 0
	v_mov_b64_e32 v[12:13], 0
	v_mov_b64_e32 v[14:15], 0
	v_mov_b64_e32 v[16:17], 0
	v_mov_b64_e32 v[18:19], 0
	v_mov_b64_e32 v[20:21], 0
	v_mov_b64_e32 v[22:23], 0
	v_mov_b64_e32 v[24:25], 0
	v_mov_b64_e32 v[26:27], 0
	v_mov_b64_e32 v[28:29], 0
	v_mov_b64_e32 v[30:31], 0
	v_mov_b64_e32 v[156:157], 0
	v_mov_b64_e32 v[158:159], 0
	v_mov_b64_e32 v[160:161], 0
	v_mov_b64_e32 v[162:163], 0
	v_mov_b64_e32 v[164:165], 0
	v_mov_b64_e32 v[166:167], 0
	v_mov_b64_e32 v[168:169], 0
	v_mov_b64_e32 v[170:171], 0
	v_mov_b64_e32 v[172:173], 0
	v_mov_b64_e32 v[174:175], 0
	v_mov_b64_e32 v[176:177], 0
	v_mov_b64_e32 v[178:179], 0
	v_mov_b64_e32 v[180:181], 0
	v_mov_b64_e32 v[182:183], 0
	v_mov_b64_e32 v[116:117], 0
	v_mov_b64_e32 v[118:119], 0
	v_cmp_lt_i32_e32 vcc, s21, v113
	s_and_saveexec_b64 s[16:17], vcc
	global_load_dwordx4 v[0:3], v[120:121], off nt
	s_mov_b64 exec, s[16:17]
	v_add_u32_e32 v113, 4, v113
	v_lshl_add_u64 v[120:121], v[120:121], 0, s[18:19]
	v_cmp_lt_i32_e32 vcc, s21, v113
	s_and_saveexec_b64 s[16:17], vcc
	global_load_dwordx4 v[4:7], v[120:121], off nt
	s_mov_b64 exec, s[16:17]
	v_add_u32_e32 v113, 4, v113
	v_lshl_add_u64 v[120:121], v[120:121], 0, s[18:19]
	v_cmp_lt_i32_e32 vcc, s21, v113
	s_and_saveexec_b64 s[16:17], vcc
	global_load_dwordx4 v[8:11], v[120:121], off nt
	s_mov_b64 exec, s[16:17]
	v_add_u32_e32 v113, 4, v113
	v_lshl_add_u64 v[120:121], v[120:121], 0, s[18:19]
	v_cmp_lt_i32_e32 vcc, s21, v113
	s_and_saveexec_b64 s[16:17], vcc
	global_load_dwordx4 v[12:15], v[120:121], off nt
	s_mov_b64 exec, s[16:17]
	v_add_u32_e32 v113, 4, v113
	v_lshl_add_u64 v[120:121], v[120:121], 0, s[18:19]
	v_cmp_lt_i32_e32 vcc, s21, v113
	s_and_saveexec_b64 s[16:17], vcc
	global_load_dwordx4 v[16:19], v[120:121], off nt
	s_mov_b64 exec, s[16:17]
	v_add_u32_e32 v113, 4, v113
	v_lshl_add_u64 v[120:121], v[120:121], 0, s[18:19]
	v_cmp_lt_i32_e32 vcc, s21, v113
	s_and_saveexec_b64 s[16:17], vcc
	global_load_dwordx4 v[20:23], v[120:121], off nt
	s_mov_b64 exec, s[16:17]
	v_add_u32_e32 v113, 4, v113
	v_lshl_add_u64 v[120:121], v[120:121], 0, s[18:19]
	v_cmp_lt_i32_e32 vcc, s21, v113
	s_and_saveexec_b64 s[16:17], vcc
	global_load_dwordx4 v[24:27], v[120:121], off nt
	s_mov_b64 exec, s[16:17]
	v_add_u32_e32 v113, 4, v113
	v_lshl_add_u64 v[120:121], v[120:121], 0, s[18:19]
	v_cmp_lt_i32_e32 vcc, s21, v113
	s_and_saveexec_b64 s[16:17], vcc
	global_load_dwordx4 v[28:31], v[120:121], off nt
	s_mov_b64 exec, s[16:17]
	v_add_u32_e32 v113, 4, v113
	v_lshl_add_u64 v[120:121], v[120:121], 0, s[18:19]
	v_cmp_lt_i32_e32 vcc, s21, v113
	s_and_saveexec_b64 s[16:17], vcc
	global_load_dwordx4 v[156:159], v[120:121], off nt
	s_mov_b64 exec, s[16:17]
	v_add_u32_e32 v113, 4, v113
	v_lshl_add_u64 v[120:121], v[120:121], 0, s[18:19]
	v_cmp_lt_i32_e32 vcc, s21, v113
	s_and_saveexec_b64 s[16:17], vcc
	global_load_dwordx4 v[160:163], v[120:121], off nt
	s_mov_b64 exec, s[16:17]
	v_add_u32_e32 v113, 4, v113
	v_lshl_add_u64 v[120:121], v[120:121], 0, s[18:19]
	v_cmp_lt_i32_e32 vcc, s21, v113
	s_and_saveexec_b64 s[16:17], vcc
	global_load_dwordx4 v[164:167], v[120:121], off nt
	s_mov_b64 exec, s[16:17]
	v_add_u32_e32 v113, 4, v113
	v_lshl_add_u64 v[120:121], v[120:121], 0, s[18:19]
	v_cmp_lt_i32_e32 vcc, s21, v113
	s_and_saveexec_b64 s[16:17], vcc
	global_load_dwordx4 v[168:171], v[120:121], off nt
	s_mov_b64 exec, s[16:17]
	v_add_u32_e32 v113, 4, v113
	v_lshl_add_u64 v[120:121], v[120:121], 0, s[18:19]
	v_cmp_lt_i32_e32 vcc, s21, v113
	s_and_saveexec_b64 s[16:17], vcc
	global_load_dwordx4 v[172:175], v[120:121], off nt
	s_mov_b64 exec, s[16:17]
	v_add_u32_e32 v113, 4, v113
	v_lshl_add_u64 v[120:121], v[120:121], 0, s[18:19]
	v_cmp_lt_i32_e32 vcc, s21, v113
	s_and_saveexec_b64 s[16:17], vcc
	global_load_dwordx4 v[176:179], v[120:121], off nt
	s_mov_b64 exec, s[16:17]
	v_add_u32_e32 v113, 4, v113
	v_lshl_add_u64 v[120:121], v[120:121], 0, s[18:19]
	v_cmp_lt_i32_e32 vcc, s21, v113
	s_and_saveexec_b64 s[16:17], vcc
	global_load_dwordx4 v[180:183], v[120:121], off nt
	s_mov_b64 exec, s[16:17]
	v_add_u32_e32 v113, 4, v113
	v_lshl_add_u64 v[120:121], v[120:121], 0, s[18:19]
	v_cmp_gt_u32_e32 vcc, 0x100, v207
	s_and_saveexec_b64 s[16:17], vcc
	v_cmp_lt_i32_e32 vcc, s21, v113
	s_and_b64 exec, exec, vcc
	global_load_dwordx4 v[116:119], v[120:121], off nt
	s_mov_b64 exec, s[16:17]
	v_add_u32_e32 v123, 0x10000, v112
	s_waitcnt vmcnt(0)
	ds_write_b128 v112, v[0:3]
	ds_write_b128 v112, v[4:7] offset:8192
	ds_write_b128 v112, v[8:11] offset:16384
	ds_write_b128 v112, v[12:15] offset:24576
	ds_write_b128 v112, v[16:19] offset:32768
	ds_write_b128 v112, v[20:23] offset:40960
	ds_write_b128 v112, v[24:27] offset:49152
	ds_write_b128 v112, v[28:31] offset:57344
	ds_write_b128 v123, v[156:159]
	ds_write_b128 v123, v[160:163] offset:8192
	ds_write_b128 v123, v[164:167] offset:16384
	ds_write_b128 v123, v[168:171] offset:24576
	ds_write_b128 v123, v[172:175] offset:32768
	ds_write_b128 v123, v[176:179] offset:40960
	ds_write_b128 v123, v[180:183] offset:49152
	v_cmp_gt_u32_e32 vcc, 0x100, v207
	s_and_saveexec_b64 s[16:17], vcc
	ds_write_b128 v123, v[116:119] offset:57344
	s_mov_b64 exec, s[16:17]

.LBB0_462:
	s_add_i32 s19, s75, s76
	s_and_b32 s20, s19, 0x1c000
	v_add_u32_e32 v112, s20, v184
	ds_read2st64_b32 v[32:33], v112 offset1:8
	ds_read2st64_b32 v[34:35], v112 offset0:16 offset1:24
	s_add_i32 s21, s19, 0x4000
	s_and_b32 s21, s21, 0x1c000
	s_xor_b32 s20, s20, 0x10000
	s_waitcnt lgkmcnt(1)
	v_lshlrev_b32_e32 v152, 16, v32
	v_and_b32_e32 v153, 0xffff0000, v32
	v_lshlrev_b32_e32 v154, 16, v33
	v_and_b32_e32 v155, 0xffff0000, v33
	ds_read2st64_b32 v[32:33], v112 offset0:32 offset1:40
	ds_read2st64_b32 v[112:113], v112 offset0:48 offset1:56
	s_waitcnt lgkmcnt(2)
	v_lshlrev_b32_e32 v150, 16, v34
	v_and_b32_e32 v151, 0xffff0000, v34
	v_lshlrev_b32_e32 v142, 16, v35
	v_and_b32_e32 v143, 0xffff0000, v35
	s_waitcnt lgkmcnt(0)
	v_lshlrev_b32_e32 v34, 16, v112
	v_and_b32_e32 v35, 0xffff0000, v112
	v_add_u32_e32 v112, s21, v184
	s_add_i32 s21, s19, 0x4800
	s_and_b32 s21, s21, 0x1c800
	v_lshlrev_b32_e32 v130, 16, v32
	v_and_b32_e32 v131, 0xffff0000, v32
	v_lshlrev_b32_e32 v128, 16, v33
	v_and_b32_e32 v129, 0xffff0000, v33
	v_lshlrev_b32_e32 v32, 16, v113
	v_and_b32_e32 v33, 0xffff0000, v113
	v_add_u32_e32 v113, s21, v184
	s_add_i32 s21, s19, 0x5000
	s_and_b32 s21, s21, 0x1d000
	v_add_u32_e32 v114, s21, v184
	s_add_i32 s21, s19, 0x5800
	s_and_b32 s21, s21, 0x1d800
	v_add_u32_e32 v115, s21, v184
	s_add_i32 s21, s19, 0x6000
	s_and_b32 s21, s21, 0x1e000
	v_add_u32_e32 v116, s21, v184
	s_add_i32 s21, s19, 0x6800
	s_and_b32 s21, s21, 0x1e800
	v_add_u32_e32 v117, s21, v184
	s_add_i32 s21, s19, 0x7000
	s_and_b32 s21, s21, 0x1f000
	v_add_u32_e32 v118, s21, v184
	s_add_i32 s21, s19, 0x7800
	s_and_b32 s21, s21, 0x1f800
	v_add_u32_e32 v119, s21, v184
	s_add_i32 s21, s19, 0x8000
	s_and_b32 s21, s21, 0x1c000
	v_add_u32_e32 v132, s21, v184
	s_add_i32 s21, s19, 0x8800
	s_and_b32 s21, s21, 0x1c800
	v_add_u32_e32 v133, s21, v184
	s_add_i32 s21, s19, 0x9000
	s_and_b32 s21, s21, 0x1d000
	v_add_u32_e32 v134, s21, v184
	s_add_i32 s21, s19, 0x9800
	s_and_b32 s21, s21, 0x1d800
	v_add_u32_e32 v135, s21, v184
	s_add_i32 s21, s19, 0xa000
	s_and_b32 s21, s21, 0x1e000
	v_add_u32_e32 v136, s21, v184
	s_add_i32 s21, s19, 0xa800
	s_and_b32 s21, s21, 0x1e800
	v_add_u32_e32 v137, s21, v184
	s_add_i32 s21, s19, 0xb000
	s_and_b32 s21, s21, 0x1f000
	v_add_u32_e32 v138, s21, v184
	s_add_i32 s21, s19, 0xb800
	s_and_b32 s21, s21, 0x1f800
	v_add_u32_e32 v139, s21, v184
	s_add_i32 s21, s19, 0xc000
	s_and_b32 s21, s21, 0x1c000
	v_add_u32_e32 v156, s21, v184
	s_add_i32 s21, s19, 0xc800
	s_and_b32 s21, s21, 0x1c800
	v_add_u32_e32 v157, s21, v184
	s_add_i32 s21, s19, 0xd000
	s_and_b32 s21, s21, 0x1d000
	v_add_u32_e32 v158, s21, v184
	s_add_i32 s21, s19, 0xd800
	s_and_b32 s21, s21, 0x1d800
	v_add_u32_e32 v159, s21, v184
	s_add_i32 s21, s19, 0xe000
	s_and_b32 s21, s21, 0x1e000
	v_add_u32_e32 v160, s21, v184
	s_add_i32 s21, s19, 0xe800
	s_and_b32 s21, s21, 0x1e800
	v_add_u32_e32 v161, s21, v184
	s_add_i32 s21, s19, 0xf000
	s_and_b32 s21, s21, 0x1f000
	v_add_u32_e32 v172, s20, v184
	s_add_i32 s20, s19, 0x11000
	v_add_u32_e32 v162, s21, v184
	s_add_i32 s21, s19, 0xf800
	s_and_b32 s20, s20, 0x1d000
	s_and_b32 s21, s21, 0x1f800
	v_add_u32_e32 v174, s20, v184
	s_add_i32 s20, s18, -7
	v_add_u32_e32 v163, s21, v184
	s_ashr_i32 s21, s20, 31
	s_lshl_b64 s[46:47], s[20:21], 11
	s_add_i32 s20, s18, -6
	s_ashr_i32 s21, s20, 31
	s_lshl_b64 s[36:37], s[20:21], 11
	s_add_i32 s20, s18, -5
	s_ashr_i32 s21, s20, 31
	s_lshl_b64 s[34:35], s[20:21], 11
	s_add_i32 s20, s18, -4
	s_ashr_i32 s21, s20, 31
	s_add_i32 s19, s19, 0x12000
	s_lshl_b64 s[30:31], s[20:21], 11
	s_add_i32 s20, s18, -3
	ds_read_b32 v120, v112
	ds_read_b32 v121, v113
	ds_read_b32 v122, v114
	ds_read_b32 v123, v115
	ds_read_b32 v124, v116
	ds_read_b32 v125, v117
	ds_read_b32 v126, v118
	ds_read_b32 v127, v119
	ds_read_b32 v140, v132
	ds_read_b32 v141, v133
	ds_read_b32 v144, v134
	ds_read_b32 v145, v135
	ds_read_b32 v146, v136
	ds_read_b32 v147, v137
	ds_read_b32 v148, v138
	ds_read_b32 v149, v139
	ds_read_b32 v164, v156
	ds_read_b32 v165, v157
	ds_read_b32 v166, v158
	ds_read_b32 v167, v159
	ds_read_b32 v168, v160
	ds_read_b32 v169, v161
	ds_read_b32 v170, v162
	ds_read_b32 v171, v163
	ds_read_b32 v173, v172
	v_add_u32_e32 v172, s76, v208
	s_and_b32 s19, s19, 0x1e000
	s_ashr_i32 s21, s20, 31
	ds_read2st64_b32 v[178:179], v172 offset1:16
	v_add_u32_e32 v175, s19, v184
	ds_read_b32 v177, v174
	ds_read_b32 v183, v175
	ds_read_b32 v209, v172 offset:8192
	s_lshl_b64 s[28:29], s[20:21], 11
	s_add_i32 s20, s18, -2
	v_pk_fma_f32 v[152:153], v[98:99], v[152:153], v[100:101]
	s_ashr_i32 s21, s20, 31
	v_pk_fma_f32 v[152:153], v[38:39], v[154:155], v[152:153]
	v_pk_fma_f32 v[154:155], v[98:99], v[154:155], v[100:101]
	s_lshl_b64 s[26:27], s[20:21], 11
	s_add_i32 s20, s18, -1
	v_pk_fma_f32 v[152:153], v[40:41], v[150:151], v[152:153]
	v_pk_fma_f32 v[154:155], v[38:39], v[150:151], v[154:155]
	v_pk_fma_f32 v[150:151], v[98:99], v[150:151], v[100:101]
	s_ashr_i32 s21, s20, 31
	s_ashr_i32 s19, s18, 31
	v_pk_fma_f32 v[152:153], v[42:43], v[142:143], v[152:153]
	v_pk_fma_f32 v[154:155], v[40:41], v[142:143], v[154:155]
	v_pk_fma_f32 v[150:151], v[38:39], v[142:143], v[150:151]
	v_pk_fma_f32 v[142:143], v[98:99], v[142:143], v[100:101]
	v_lshl_add_u64 v[210:211], v[36:37], 0, s[46:47]
	v_lshl_add_u64 v[212:213], v[36:37], 0, s[36:37]
	s_lshl_b64 s[24:25], s[20:21], 11
	s_lshl_b64 s[20:21], s[18:19], 11
	v_pk_fma_f32 v[152:153], v[44:45], v[130:131], v[152:153]
	v_pk_fma_f32 v[154:155], v[42:43], v[130:131], v[154:155]
	v_pk_fma_f32 v[150:151], v[40:41], v[130:131], v[150:151]
	v_pk_fma_f32 v[142:143], v[38:39], v[130:131], v[142:143]
	v_pk_fma_f32 v[130:131], v[98:99], v[130:131], v[100:101]
	s_waitcnt lgkmcnt(3)
	v_lshlrev_b32_e32 v174, 16, v178
	v_and_b32_e32 v175, 0xffff0000, v178
	v_lshlrev_b32_e32 v180, 16, v179
	v_and_b32_e32 v181, 0xffff0000, v179
	s_waitcnt lgkmcnt(0)
	v_lshlrev_b32_e32 v178, 16, v209
	v_and_b32_e32 v179, 0xffff0000, v209
	v_lshl_add_u64 v[218:219], v[36:37], 0, s[34:35]
	v_lshl_add_u64 v[220:221], v[36:37], 0, s[30:31]
	v_lshl_add_u64 v[222:223], v[36:37], 0, s[28:29]
	v_lshl_add_u64 v[224:225], v[36:37], 0, s[26:27]
	v_lshl_add_u64 v[226:227], v[36:37], 0, s[24:25]
	v_lshl_add_u64 v[228:229], v[36:37], 0, s[20:21]
	global_load_dword v216, v[210:211], off nt
	global_load_dword v215, v[212:213], off nt
	global_load_dword v214, v[218:219], off nt
	s_nop 0
	global_load_dword v213, v[220:221], off nt
	global_load_dword v212, v[222:223], off nt
	global_load_dword v211, v[224:225], off nt
	global_load_dword v210, v[226:227], off nt
	global_load_dword v209, v[228:229], off nt
	v_pk_fma_f32 v[152:153], v[46:47], v[128:129], v[152:153]
	v_pk_fma_f32 v[154:155], v[44:45], v[128:129], v[154:155]
	v_pk_fma_f32 v[150:151], v[42:43], v[128:129], v[150:151]
	v_pk_fma_f32 v[142:143], v[40:41], v[128:129], v[142:143]
	v_pk_fma_f32 v[130:131], v[38:39], v[128:129], v[130:131]
	v_pk_fma_f32 v[128:129], v[98:99], v[128:129], v[100:101]
	v_pk_fma_f32 v[152:153], v[48:49], v[34:35], v[152:153]
	v_pk_fma_f32 v[154:155], v[46:47], v[34:35], v[154:155]
	v_pk_fma_f32 v[150:151], v[44:45], v[34:35], v[150:151]
	v_pk_fma_f32 v[142:143], v[42:43], v[34:35], v[142:143]
	v_pk_fma_f32 v[130:131], v[40:41], v[34:35], v[130:131]
	v_pk_fma_f32 v[128:129], v[38:39], v[34:35], v[128:129]
	v_pk_fma_f32 v[34:35], v[98:99], v[34:35], v[100:101]
	v_lshlrev_b32_e32 v112, 16, v120
	v_and_b32_e32 v113, 0xffff0000, v120
	v_pk_fma_f32 v[152:153], v[50:51], v[32:33], v[152:153]
	v_pk_fma_f32 v[154:155], v[48:49], v[32:33], v[154:155]
	v_pk_fma_f32 v[150:151], v[46:47], v[32:33], v[150:151]
	v_pk_fma_f32 v[142:143], v[44:45], v[32:33], v[142:143]
	v_pk_fma_f32 v[130:131], v[42:43], v[32:33], v[130:131]
	v_pk_fma_f32 v[128:129], v[40:41], v[32:33], v[128:129]
	v_pk_fma_f32 v[34:35], v[38:39], v[32:33], v[34:35]
	v_pk_fma_f32 v[32:33], v[98:99], v[32:33], v[100:101]
	v_lshlrev_b32_e32 v114, 16, v121
	v_and_b32_e32 v115, 0xffff0000, v121
	v_pk_fma_f32 v[152:153], v[52:53], v[112:113], v[152:153]
	v_pk_fma_f32 v[154:155], v[50:51], v[112:113], v[154:155]
	v_pk_fma_f32 v[150:151], v[48:49], v[112:113], v[150:151]
	v_pk_fma_f32 v[142:143], v[46:47], v[112:113], v[142:143]
	v_pk_fma_f32 v[130:131], v[44:45], v[112:113], v[130:131]
	v_pk_fma_f32 v[128:129], v[42:43], v[112:113], v[128:129]
	v_pk_fma_f32 v[34:35], v[40:41], v[112:113], v[34:35]
	v_pk_fma_f32 v[32:33], v[38:39], v[112:113], v[32:33]
	v_lshlrev_b32_e32 v116, 16, v122
	v_and_b32_e32 v117, 0xffff0000, v122
	v_pk_fma_f32 v[152:153], v[54:55], v[114:115], v[152:153]
	v_pk_fma_f32 v[154:155], v[52:53], v[114:115], v[154:155]
	v_pk_fma_f32 v[150:151], v[50:51], v[114:115], v[150:151]
	v_pk_fma_f32 v[142:143], v[48:49], v[114:115], v[142:143]
	v_pk_fma_f32 v[130:131], v[46:47], v[114:115], v[130:131]
	v_pk_fma_f32 v[128:129], v[44:45], v[114:115], v[128:129]
	v_pk_fma_f32 v[34:35], v[42:43], v[114:115], v[34:35]
	v_pk_fma_f32 v[32:33], v[40:41], v[114:115], v[32:33]
	v_lshlrev_b32_e32 v118, 16, v123
	v_and_b32_e32 v119, 0xffff0000, v123
	v_pk_fma_f32 v[152:153], v[56:57], v[116:117], v[152:153]
	v_pk_fma_f32 v[154:155], v[54:55], v[116:117], v[154:155]
	v_pk_fma_f32 v[150:151], v[52:53], v[116:117], v[150:151]
	v_pk_fma_f32 v[142:143], v[50:51], v[116:117], v[142:143]
	v_pk_fma_f32 v[130:131], v[48:49], v[116:117], v[130:131]
	v_pk_fma_f32 v[128:129], v[46:47], v[116:117], v[128:129]
	v_pk_fma_f32 v[34:35], v[44:45], v[116:117], v[34:35]
	v_pk_fma_f32 v[32:33], v[42:43], v[116:117], v[32:33]
	v_lshlrev_b32_e32 v120, 16, v124
	v_and_b32_e32 v121, 0xffff0000, v124
	v_pk_fma_f32 v[152:153], v[58:59], v[118:119], v[152:153]
	v_pk_fma_f32 v[154:155], v[56:57], v[118:119], v[154:155]
	v_pk_fma_f32 v[150:151], v[54:55], v[118:119], v[150:151]
	v_pk_fma_f32 v[142:143], v[52:53], v[118:119], v[142:143]
	v_pk_fma_f32 v[130:131], v[50:51], v[118:119], v[130:131]
	v_pk_fma_f32 v[128:129], v[48:49], v[118:119], v[128:129]
	v_pk_fma_f32 v[34:35], v[46:47], v[118:119], v[34:35]
	v_pk_fma_f32 v[32:33], v[44:45], v[118:119], v[32:33]
	v_lshlrev_b32_e32 v122, 16, v125
	v_and_b32_e32 v123, 0xffff0000, v125
	v_pk_fma_f32 v[152:153], v[60:61], v[120:121], v[152:153]
	v_pk_fma_f32 v[154:155], v[58:59], v[120:121], v[154:155]
	v_pk_fma_f32 v[150:151], v[56:57], v[120:121], v[150:151]
	v_pk_fma_f32 v[142:143], v[54:55], v[120:121], v[142:143]
	v_pk_fma_f32 v[130:131], v[52:53], v[120:121], v[130:131]
	v_pk_fma_f32 v[128:129], v[50:51], v[120:121], v[128:129]
	v_pk_fma_f32 v[34:35], v[48:49], v[120:121], v[34:35]
	v_pk_fma_f32 v[32:33], v[46:47], v[120:121], v[32:33]
	v_lshlrev_b32_e32 v124, 16, v126
	v_and_b32_e32 v125, 0xffff0000, v126
	v_pk_fma_f32 v[152:153], v[62:63], v[122:123], v[152:153]
	v_pk_fma_f32 v[154:155], v[60:61], v[122:123], v[154:155]
	v_pk_fma_f32 v[150:151], v[58:59], v[122:123], v[150:151]
	v_pk_fma_f32 v[142:143], v[56:57], v[122:123], v[142:143]
	v_pk_fma_f32 v[130:131], v[54:55], v[122:123], v[130:131]
	v_pk_fma_f32 v[128:129], v[52:53], v[122:123], v[128:129]
	v_pk_fma_f32 v[34:35], v[50:51], v[122:123], v[34:35]
	v_pk_fma_f32 v[32:33], v[48:49], v[122:123], v[32:33]
	v_lshlrev_b32_e32 v126, 16, v127
	v_and_b32_e32 v127, 0xffff0000, v127
	v_pk_fma_f32 v[152:153], v[64:65], v[124:125], v[152:153]
	v_pk_fma_f32 v[154:155], v[62:63], v[124:125], v[154:155]
	v_pk_fma_f32 v[150:151], v[60:61], v[124:125], v[150:151]
	v_pk_fma_f32 v[142:143], v[58:59], v[124:125], v[142:143]
	v_pk_fma_f32 v[130:131], v[56:57], v[124:125], v[130:131]
	v_pk_fma_f32 v[128:129], v[54:55], v[124:125], v[128:129]
	v_pk_fma_f32 v[34:35], v[52:53], v[124:125], v[34:35]
	v_pk_fma_f32 v[32:33], v[50:51], v[124:125], v[32:33]
	v_lshlrev_b32_e32 v132, 16, v140
	v_and_b32_e32 v133, 0xffff0000, v140
	v_pk_fma_f32 v[152:153], v[66:67], v[126:127], v[152:153]
	v_pk_fma_f32 v[154:155], v[64:65], v[126:127], v[154:155]
	v_pk_fma_f32 v[150:151], v[62:63], v[126:127], v[150:151]
	v_pk_fma_f32 v[142:143], v[60:61], v[126:127], v[142:143]
	v_pk_fma_f32 v[130:131], v[58:59], v[126:127], v[130:131]
	v_pk_fma_f32 v[128:129], v[56:57], v[126:127], v[128:129]
	v_pk_fma_f32 v[34:35], v[54:55], v[126:127], v[34:35]
	v_pk_fma_f32 v[32:33], v[52:53], v[126:127], v[32:33]
	v_lshlrev_b32_e32 v134, 16, v141
	v_and_b32_e32 v135, 0xffff0000, v141
	v_pk_fma_f32 v[152:153], v[68:69], v[132:133], v[152:153]
	v_pk_fma_f32 v[154:155], v[66:67], v[132:133], v[154:155]
	v_pk_fma_f32 v[150:151], v[64:65], v[132:133], v[150:151]
	v_pk_fma_f32 v[142:143], v[62:63], v[132:133], v[142:143]
	v_pk_fma_f32 v[130:131], v[60:61], v[132:133], v[130:131]
	v_pk_fma_f32 v[128:129], v[58:59], v[132:133], v[128:129]
	v_pk_fma_f32 v[34:35], v[56:57], v[132:133], v[34:35]
	v_pk_fma_f32 v[32:33], v[54:55], v[132:133], v[32:33]
	v_lshlrev_b32_e32 v136, 16, v144
	v_and_b32_e32 v137, 0xffff0000, v144
	v_pk_fma_f32 v[152:153], v[70:71], v[134:135], v[152:153]
	v_pk_fma_f32 v[154:155], v[68:69], v[134:135], v[154:155]
	v_pk_fma_f32 v[150:151], v[66:67], v[134:135], v[150:151]
	v_pk_fma_f32 v[142:143], v[64:65], v[134:135], v[142:143]
	v_pk_fma_f32 v[130:131], v[62:63], v[134:135], v[130:131]
	v_pk_fma_f32 v[128:129], v[60:61], v[134:135], v[128:129]
	v_pk_fma_f32 v[34:35], v[58:59], v[134:135], v[34:35]
	v_pk_fma_f32 v[32:33], v[56:57], v[134:135], v[32:33]
	v_lshlrev_b32_e32 v138, 16, v145
	v_and_b32_e32 v139, 0xffff0000, v145
	v_pk_fma_f32 v[152:153], v[72:73], v[136:137], v[152:153]
	v_pk_fma_f32 v[154:155], v[70:71], v[136:137], v[154:155]
	v_pk_fma_f32 v[150:151], v[68:69], v[136:137], v[150:151]
	v_pk_fma_f32 v[142:143], v[66:67], v[136:137], v[142:143]
	v_pk_fma_f32 v[130:131], v[64:65], v[136:137], v[130:131]
	v_pk_fma_f32 v[128:129], v[62:63], v[136:137], v[128:129]
	v_pk_fma_f32 v[34:35], v[60:61], v[136:137], v[34:35]
	v_pk_fma_f32 v[32:33], v[58:59], v[136:137], v[32:33]
	v_lshlrev_b32_e32 v140, 16, v146
	v_and_b32_e32 v141, 0xffff0000, v146
	v_pk_fma_f32 v[152:153], v[74:75], v[138:139], v[152:153]
	v_pk_fma_f32 v[154:155], v[72:73], v[138:139], v[154:155]
	v_pk_fma_f32 v[150:151], v[70:71], v[138:139], v[150:151]
	v_pk_fma_f32 v[142:143], v[68:69], v[138:139], v[142:143]
	v_pk_fma_f32 v[130:131], v[66:67], v[138:139], v[130:131]
	v_pk_fma_f32 v[128:129], v[64:65], v[138:139], v[128:129]
	v_pk_fma_f32 v[34:35], v[62:63], v[138:139], v[34:35]
	v_pk_fma_f32 v[32:33], v[60:61], v[138:139], v[32:33]
	v_lshlrev_b32_e32 v144, 16, v147
	v_and_b32_e32 v145, 0xffff0000, v147
	v_pk_fma_f32 v[152:153], v[76:77], v[140:141], v[152:153]
	v_pk_fma_f32 v[154:155], v[74:75], v[140:141], v[154:155]
	v_pk_fma_f32 v[150:151], v[72:73], v[140:141], v[150:151]
	v_pk_fma_f32 v[142:143], v[70:71], v[140:141], v[142:143]
	v_pk_fma_f32 v[130:131], v[68:69], v[140:141], v[130:131]
	v_pk_fma_f32 v[128:129], v[66:67], v[140:141], v[128:129]
	v_pk_fma_f32 v[34:35], v[64:65], v[140:141], v[34:35]
	v_pk_fma_f32 v[32:33], v[62:63], v[140:141], v[32:33]
	v_lshlrev_b32_e32 v146, 16, v148
	v_and_b32_e32 v147, 0xffff0000, v148
	v_pk_fma_f32 v[152:153], v[78:79], v[144:145], v[152:153]
	v_pk_fma_f32 v[154:155], v[76:77], v[144:145], v[154:155]
	v_pk_fma_f32 v[150:151], v[74:75], v[144:145], v[150:151]
	v_pk_fma_f32 v[142:143], v[72:73], v[144:145], v[142:143]
	v_pk_fma_f32 v[130:131], v[70:71], v[144:145], v[130:131]
	v_pk_fma_f32 v[128:129], v[68:69], v[144:145], v[128:129]
	v_pk_fma_f32 v[34:35], v[66:67], v[144:145], v[34:35]
	v_pk_fma_f32 v[32:33], v[64:65], v[144:145], v[32:33]
	v_lshlrev_b32_e32 v148, 16, v149
	v_and_b32_e32 v149, 0xffff0000, v149
	v_pk_fma_f32 v[152:153], v[80:81], v[146:147], v[152:153]
	v_pk_fma_f32 v[154:155], v[78:79], v[146:147], v[154:155]
	v_pk_fma_f32 v[150:151], v[76:77], v[146:147], v[150:151]
	v_pk_fma_f32 v[142:143], v[74:75], v[146:147], v[142:143]
	v_pk_fma_f32 v[130:131], v[72:73], v[146:147], v[130:131]
	v_pk_fma_f32 v[128:129], v[70:71], v[146:147], v[128:129]
	v_pk_fma_f32 v[34:35], v[68:69], v[146:147], v[34:35]
	v_pk_fma_f32 v[32:33], v[66:67], v[146:147], v[32:33]
	v_lshlrev_b32_e32 v156, 16, v164
	v_and_b32_e32 v157, 0xffff0000, v164
	v_pk_fma_f32 v[152:153], v[82:83], v[148:149], v[152:153]
	v_pk_fma_f32 v[154:155], v[80:81], v[148:149], v[154:155]
	v_pk_fma_f32 v[150:151], v[78:79], v[148:149], v[150:151]
	v_pk_fma_f32 v[142:143], v[76:77], v[148:149], v[142:143]
	v_pk_fma_f32 v[130:131], v[74:75], v[148:149], v[130:131]
	v_pk_fma_f32 v[128:129], v[72:73], v[148:149], v[128:129]
	v_pk_fma_f32 v[34:35], v[70:71], v[148:149], v[34:35]
	v_pk_fma_f32 v[32:33], v[68:69], v[148:149], v[32:33]
	v_lshlrev_b32_e32 v158, 16, v165
	v_and_b32_e32 v159, 0xffff0000, v165
	v_pk_fma_f32 v[152:153], v[84:85], v[156:157], v[152:153]
	v_pk_fma_f32 v[154:155], v[82:83], v[156:157], v[154:155]
	v_pk_fma_f32 v[150:151], v[80:81], v[156:157], v[150:151]
	v_pk_fma_f32 v[142:143], v[78:79], v[156:157], v[142:143]
	v_pk_fma_f32 v[130:131], v[76:77], v[156:157], v[130:131]
	v_pk_fma_f32 v[128:129], v[74:75], v[156:157], v[128:129]
	v_pk_fma_f32 v[34:35], v[72:73], v[156:157], v[34:35]
	v_pk_fma_f32 v[32:33], v[70:71], v[156:157], v[32:33]
	v_lshlrev_b32_e32 v160, 16, v166
	v_and_b32_e32 v161, 0xffff0000, v166
	v_pk_fma_f32 v[152:153], v[86:87], v[158:159], v[152:153]
	v_pk_fma_f32 v[154:155], v[84:85], v[158:159], v[154:155]
	v_pk_fma_f32 v[150:151], v[82:83], v[158:159], v[150:151]
	v_pk_fma_f32 v[142:143], v[80:81], v[158:159], v[142:143]
	v_pk_fma_f32 v[130:131], v[78:79], v[158:159], v[130:131]
	v_pk_fma_f32 v[128:129], v[76:77], v[158:159], v[128:129]
	v_pk_fma_f32 v[34:35], v[74:75], v[158:159], v[34:35]
	v_pk_fma_f32 v[32:33], v[72:73], v[158:159], v[32:33]
	v_lshlrev_b32_e32 v162, 16, v167
	v_and_b32_e32 v163, 0xffff0000, v167
	v_pk_fma_f32 v[152:153], v[88:89], v[160:161], v[152:153]
	v_pk_fma_f32 v[154:155], v[86:87], v[160:161], v[154:155]
	v_pk_fma_f32 v[150:151], v[84:85], v[160:161], v[150:151]
	v_pk_fma_f32 v[142:143], v[82:83], v[160:161], v[142:143]
	v_pk_fma_f32 v[130:131], v[80:81], v[160:161], v[130:131]
	v_pk_fma_f32 v[128:129], v[78:79], v[160:161], v[128:129]
	v_pk_fma_f32 v[34:35], v[76:77], v[160:161], v[34:35]
	v_pk_fma_f32 v[32:33], v[74:75], v[160:161], v[32:33]
	v_lshlrev_b32_e32 v164, 16, v168
	v_and_b32_e32 v165, 0xffff0000, v168
	v_pk_fma_f32 v[152:153], v[90:91], v[162:163], v[152:153]
	v_pk_fma_f32 v[154:155], v[88:89], v[162:163], v[154:155]
	v_pk_fma_f32 v[150:151], v[86:87], v[162:163], v[150:151]
	v_pk_fma_f32 v[142:143], v[84:85], v[162:163], v[142:143]
	v_pk_fma_f32 v[130:131], v[82:83], v[162:163], v[130:131]
	v_pk_fma_f32 v[128:129], v[80:81], v[162:163], v[128:129]
	v_pk_fma_f32 v[34:35], v[78:79], v[162:163], v[34:35]
	v_pk_fma_f32 v[32:33], v[76:77], v[162:163], v[32:33]
	v_lshlrev_b32_e32 v166, 16, v169
	v_and_b32_e32 v167, 0xffff0000, v169
	v_pk_fma_f32 v[152:153], v[92:93], v[164:165], v[152:153]
	v_pk_fma_f32 v[154:155], v[90:91], v[164:165], v[154:155]
	v_pk_fma_f32 v[150:151], v[88:89], v[164:165], v[150:151]
	v_pk_fma_f32 v[142:143], v[86:87], v[164:165], v[142:143]
	v_pk_fma_f32 v[130:131], v[84:85], v[164:165], v[130:131]
	v_pk_fma_f32 v[128:129], v[82:83], v[164:165], v[128:129]
	v_pk_fma_f32 v[34:35], v[80:81], v[164:165], v[34:35]
	v_pk_fma_f32 v[32:33], v[78:79], v[164:165], v[32:33]
	v_lshlrev_b32_e32 v168, 16, v170
	v_and_b32_e32 v169, 0xffff0000, v170
	v_pk_fma_f32 v[152:153], v[94:95], v[166:167], v[152:153]
	v_pk_fma_f32 v[154:155], v[92:93], v[166:167], v[154:155]
	v_pk_fma_f32 v[150:151], v[90:91], v[166:167], v[150:151]
	v_pk_fma_f32 v[142:143], v[88:89], v[166:167], v[142:143]
	v_pk_fma_f32 v[130:131], v[86:87], v[166:167], v[130:131]
	v_pk_fma_f32 v[128:129], v[84:85], v[166:167], v[128:129]
	v_pk_fma_f32 v[34:35], v[82:83], v[166:167], v[34:35]
	v_pk_fma_f32 v[32:33], v[80:81], v[166:167], v[32:33]
	v_lshlrev_b32_e32 v170, 16, v171
	v_and_b32_e32 v171, 0xffff0000, v171
	v_pk_fma_f32 v[152:153], v[96:97], v[168:169], v[152:153]
	v_pk_fma_f32 v[154:155], v[94:95], v[168:169], v[154:155]
	v_pk_fma_f32 v[150:151], v[92:93], v[168:169], v[150:151]
	v_pk_fma_f32 v[142:143], v[90:91], v[168:169], v[142:143]
	v_pk_fma_f32 v[130:131], v[88:89], v[168:169], v[130:131]
	v_pk_fma_f32 v[128:129], v[86:87], v[168:169], v[128:129]
	v_pk_fma_f32 v[34:35], v[84:85], v[168:169], v[34:35]
	v_pk_fma_f32 v[32:33], v[82:83], v[168:169], v[32:33]
	v_lshlrev_b32_e32 v172, 16, v173
	v_and_b32_e32 v173, 0xffff0000, v173
	v_pk_fma_f32 v[154:155], v[96:97], v[170:171], v[154:155]
	v_pk_fma_f32 v[150:151], v[94:95], v[170:171], v[150:151]
	v_pk_fma_f32 v[142:143], v[92:93], v[170:171], v[142:143]
	v_pk_fma_f32 v[130:131], v[90:91], v[170:171], v[130:131]
	v_pk_fma_f32 v[128:129], v[88:89], v[170:171], v[128:129]
	v_pk_fma_f32 v[34:35], v[86:87], v[170:171], v[34:35]
	v_pk_fma_f32 v[32:33], v[84:85], v[170:171], v[32:33]
	v_pk_mul_f32 v[112:113], v[152:153], v[152:153]
	v_pk_fma_f32 v[150:151], v[96:97], v[172:173], v[150:151]
	v_pk_fma_f32 v[142:143], v[94:95], v[172:173], v[142:143]
	v_pk_fma_f32 v[130:131], v[92:93], v[172:173], v[130:131]
	v_pk_fma_f32 v[128:129], v[90:91], v[172:173], v[128:129]
	v_pk_fma_f32 v[34:35], v[88:89], v[172:173], v[34:35]
	v_pk_fma_f32 v[32:33], v[86:87], v[172:173], v[32:33]
	v_add_f32_e32 v115, v112, v113
	v_pk_mul_f32 v[112:113], v[154:155], v[154:155]
	v_lshlrev_b32_e32 v176, 16, v177
	v_and_b32_e32 v177, 0xffff0000, v177
	v_pk_fma_f32 v[142:143], v[96:97], v[174:175], v[142:143]
	v_pk_fma_f32 v[130:131], v[94:95], v[174:175], v[130:131]
	v_pk_fma_f32 v[128:129], v[92:93], v[174:175], v[128:129]
	v_pk_fma_f32 v[34:35], v[90:91], v[174:175], v[34:35]
	v_pk_fma_f32 v[32:33], v[88:89], v[174:175], v[32:33]
	v_add_f32_e32 v117, v112, v113
	v_pk_mul_f32 v[112:113], v[150:151], v[150:151]
	v_pk_fma_f32 v[130:131], v[96:97], v[176:177], v[130:131]
	v_pk_fma_f32 v[128:129], v[94:95], v[176:177], v[128:129]
	v_pk_fma_f32 v[34:35], v[92:93], v[176:177], v[34:35]
	v_pk_fma_f32 v[32:33], v[90:91], v[176:177], v[32:33]
	v_add_f32_e32 v119, v112, v113
	v_pk_mul_f32 v[112:113], v[142:143], v[142:143]
	v_lshlrev_b32_e32 v182, 16, v183
	v_and_b32_e32 v183, 0xffff0000, v183
	v_pk_fma_f32 v[128:129], v[96:97], v[180:181], v[128:129]
	v_pk_fma_f32 v[34:35], v[94:95], v[180:181], v[34:35]
	v_pk_fma_f32 v[32:33], v[92:93], v[180:181], v[32:33]
	v_add_f32_e32 v121, v112, v113
	v_pk_mul_f32 v[112:113], v[130:131], v[130:131]
	v_pk_fma_f32 v[34:35], v[96:97], v[182:183], v[34:35]
	v_pk_fma_f32 v[32:33], v[94:95], v[182:183], v[32:33]
	v_add_f32_e32 v123, v112, v113
	v_pk_mul_f32 v[112:113], v[128:129], v[128:129]
	v_pk_fma_f32 v[32:33], v[96:97], v[178:179], v[32:33]
	v_add_f32_e32 v125, v112, v113
	v_pk_mul_f32 v[112:113], v[34:35], v[34:35]
	v_add_f32_e32 v114, v152, v153
	v_add_f32_e32 v122, v130, v131
	v_add_f32_e32 v127, v112, v113
	v_pk_mul_f32 v[112:113], v[32:33], v[32:33]
	v_add_f32_e32 v116, v154, v155
	v_add_f32_e32 v112, v112, v113
	v_cndmask_b32_e64 v113, v122, v114, s[2:3]
	v_cndmask_b32_e64 v114, v114, v122, s[2:3]
	ds_bpermute_b32 v114, v197, v114
	v_cndmask_b32_e64 v122, v115, v123, s[2:3]
	ds_bpermute_b32 v122, v197, v122
	v_add_f32_e32 v124, v128, v129
	v_add_f32_e32 v118, v150, v151
	v_add_f32_e32 v126, v34, v35
	v_cndmask_b32_e64 v133, v116, v124, s[2:3]
	s_waitcnt lgkmcnt(1)
	v_add_f32_e32 v113, v113, v114
	v_cndmask_b32_e64 v114, v123, v115, s[2:3]
	v_cndmask_b32_e64 v115, v124, v116, s[2:3]
	v_cndmask_b32_e64 v116, v125, v117, s[2:3]
	v_cndmask_b32_e64 v117, v117, v125, s[2:3]
	s_waitcnt lgkmcnt(0)
	v_add_f32_e32 v114, v114, v122
	ds_bpermute_b32 v117, v197, v117
	v_cndmask_b32_e64 v122, v118, v126, s[2:3]
	ds_bpermute_b32 v122, v197, v122
	v_add_f32_e32 v120, v142, v143
	v_add_f32_e32 v132, v32, v33
	s_waitcnt lgkmcnt(1)
	v_add_f32_e32 v116, v116, v117
	v_cndmask_b32_e64 v117, v126, v118, s[2:3]
	v_cndmask_b32_e64 v123, v119, v127, s[2:3]
	s_waitcnt lgkmcnt(0)
	v_add_f32_e32 v117, v117, v122
	v_cndmask_b32_e64 v118, v127, v119, s[2:3]
	v_cndmask_b32_e64 v119, v132, v120, s[2:3]
	v_cndmask_b32_e64 v120, v120, v132, s[2:3]
	v_cndmask_b32_e64 v122, v121, v112, s[2:3]
	ds_bpermute_b32 v133, v197, v133
	ds_bpermute_b32 v123, v197, v123
	ds_bpermute_b32 v120, v197, v120
	ds_bpermute_b32 v122, v197, v122
	v_cndmask_b32_e64 v112, v112, v121, s[2:3]
	s_waitcnt lgkmcnt(3)
	v_add_f32_e32 v115, v115, v133
	s_waitcnt lgkmcnt(2)
	v_add_f32_e32 v118, v118, v123
	s_waitcnt lgkmcnt(1)
	v_add_f32_e32 v119, v119, v120
	s_waitcnt lgkmcnt(0)
	v_add_f32_e32 v112, v112, v122
	v_cndmask_b32_e64 v123, v113, v117, s[4:5]
	v_cndmask_b32_e64 v113, v117, v113, s[4:5]
	v_cndmask_b32_e64 v117, v118, v114, s[4:5]
	v_cndmask_b32_e64 v114, v114, v118, s[4:5]
	v_cndmask_b32_e64 v118, v115, v119, s[4:5]
	v_cndmask_b32_e64 v120, v116, v112, s[4:5]
	ds_bpermute_b32 v123, v198, v123
	ds_bpermute_b32 v114, v198, v114
	ds_bpermute_b32 v118, v198, v118
	ds_bpermute_b32 v120, v198, v120
	v_cndmask_b32_e64 v115, v119, v115, s[4:5]
	v_cndmask_b32_e64 v112, v112, v116, s[4:5]
	s_waitcnt lgkmcnt(3)
	v_add_f32_e32 v113, v113, v123
	s_waitcnt lgkmcnt(2)
	v_add_f32_e32 v114, v117, v114
	s_waitcnt lgkmcnt(1)
	v_add_f32_e32 v115, v115, v118
	s_waitcnt lgkmcnt(0)
	v_add_f32_e32 v112, v112, v120
	v_cndmask_b32_e64 v116, v113, v115, s[6:7]
	v_cndmask_b32_e64 v117, v114, v112, s[6:7]
	ds_bpermute_b32 v116, v199, v116
	ds_bpermute_b32 v117, v199, v117
	v_cndmask_b32_e64 v113, v115, v113, s[6:7]
	v_cndmask_b32_e64 v112, v112, v114, s[6:7]
	s_waitcnt lgkmcnt(1)
	v_add_f32_e32 v113, v113, v116
	s_waitcnt lgkmcnt(0)
	v_add_f32_e32 v112, v112, v117
	v_cndmask_b32_e64 v114, v113, v112, s[8:9]
	ds_bpermute_b32 v114, v200, v114
	v_cndmask_b32_e64 v112, v112, v113, s[8:9]
	s_waitcnt lgkmcnt(0)
	v_add_f32_e32 v112, v112, v114
	ds_bpermute_b32 v113, v201, v112
	s_waitcnt lgkmcnt(0)
	v_add_f32_e32 v112, v112, v113
	ds_bpermute_b32 v113, v202, v112
	s_and_saveexec_b64 s[48:49], s[10:11]
	s_cbranch_execz .LBB0_464
	s_waitcnt lgkmcnt(0)
	v_add_f32_e32 v112, v112, v113
	ds_write_b32 v185, v112

.LBB0_751:
	v_readfirstlane_b32 s1, v207
	s_lshr_b32 s0, s1, 6
	s_lshl_b32 s37, s36, 8
	s_lshl_b32 s79, s0, 5
	s_add_i32 s37, s79, s37
	v_or_b32_e32 v188, s37, v209
	v_add_u32_e32 v176, s46, v188
	v_lshlrev_b64 v[0:1], 11, v[176:177]
	v_lshl_add_u64 v[4:5], v[182:183], 0, v[0:1]
	global_load_dwordx4 v[144:147], v[4:5], off
	global_load_dwordx4 v[148:151], v[4:5], off offset:32
	global_load_dwordx4 v[152:155], v[4:5], off offset:64
	global_load_dwordx4 v[156:159], v[4:5], off offset:96
	global_load_dwordx4 v[160:163], v[4:5], off offset:128
	global_load_dwordx4 v[164:167], v[4:5], off offset:160
	global_load_dwordx4 v[168:171], v[4:5], off offset:192
	global_load_dwordx4 v[172:175], v[4:5], off offset:224
	s_lshl_b32 s37, s0, 13
	v_add_u32_e32 v189, s37, v211
	s_lshl_b32 s37, s0, 3
	v_or_b32_e32 v16, s37, v212
	v_bitop3_b32 v17, s37, v207, v212 bitop3:0x36
	s_lshr_b32 s1, s1, 5
	v_lshlrev_b32_e32 v16, 11, v16
	v_lshlrev_b32_e32 v17, 4, v17
	s_and_b32 s1, s1, 2
	v_and_or_b32 v176, v17, s70, v16
	v_bitop3_b32 v17, s1, v213, v214 bitop3:0x36
	s_or_b32 s1, s37, 4
	s_lshl_b32 s83, s36, 2
	v_lshl_or_b32 v190, v17, 4, v16
	v_or_b32_e32 v16, s1, v212
	v_bitop3_b32 v17, s1, v207, v212 bitop3:0x36
	s_lshl_b32 s38, s36, 3
	v_lshlrev_b32_e32 v16, 11, v16
	v_lshlrev_b32_e32 v17, 4, v17
	s_bfe_u32 s1, s1, 0x20002
	s_or_b32 s86, s83, 3
	v_and_or_b32 v192, v17, s70, v16
	v_bitop3_b32 v17, s1, v213, v214 bitop3:0x36
	s_add_i32 s84, s0, s38
	s_add_i32 s85, s83, 4
	s_lshl_b32 s1, s86, 17
	s_add_u32 s40, s76, s1
	s_addc_u32 s41, s77, 0
	s_add_u32 s66, s81, s1
	s_addc_u32 s67, s82, 0
	s_lshl_b32 s87, s0, 11
	s_add_i32 s88, s87, 0
	s_lshl_b32 s0, s36, 19
	s_add_i32 s89, s88, 0xc000
	s_or_b32 s90, s87, 0x400
	s_add_i32 s91, s88, 0x400
	s_add_i32 s92, s88, 0xc400
	s_or_b32 s36, s0, 0x40000
	s_mov_b32 m0, s88
	s_add_u32 s0, s76, s36
	s_addc_u32 s1, s77, 0
	s_add_u32 s36, s81, s36
	v_lshl_or_b32 v194, v17, 4, v16
	s_addc_u32 s37, s82, 0
	s_add_i32 s93, s88, 0x4000
	s_add_i32 s94, s71, s87
	s_add_i32 s95, s88, 0x4400
	s_add_i32 s96, s71, s90
	v_mov_b32_e32 v185, v184
	v_mov_b32_e32 v96, v177
	v_mov_b32_e32 v97, v177
	v_mov_b32_e32 v110, v177
	v_mov_b32_e32 v111, v177
	v_mov_b32_e32 v98, v177
	v_mov_b32_e32 v99, v177
	v_mov_b32_e32 v100, v177
	v_mov_b32_e32 v101, v177
	v_mov_b32_e32 v102, v177
	v_mov_b32_e32 v103, v177
	v_mov_b32_e32 v104, v177
	v_mov_b32_e32 v105, v177
	v_mov_b32_e32 v106, v177
	v_mov_b32_e32 v107, v177
	v_mov_b32_e32 v108, v177
	v_mov_b32_e32 v109, v177
	v_mov_b64_e32 v[64:65], v[96:97]
	v_mov_b64_e32 v[80:81], v[96:97]
	v_mov_b64_e32 v[32:33], v[96:97]
	v_mov_b64_e32 v[48:49], v[96:97]
	v_mov_b64_e32 v[126:127], v[110:111]
	v_mov_b32_e32 v191, v177
	v_mov_b32_e32 v193, v177
	v_mov_b32_e32 v195, v177
	s_sub_i32 s97, s79, 64
	s_add_i32 s65, s79, 0xffffffa0
	s_or_b32 s38, s38, 6
	s_add_i32 s39, s79, 0xffffff80
	v_mov_b32_e32 v196, v177
	v_mov_b32_e32 v197, v177
	v_mov_b32_e32 v199, 0xf149f2ca
	v_mov_b32_e32 v201, 0xf149f2ca
	v_mov_b64_e32 v[66:67], v[98:99]
	v_mov_b64_e32 v[68:69], v[100:101]
	v_mov_b64_e32 v[70:71], v[102:103]
	v_mov_b64_e32 v[72:73], v[104:105]
	v_mov_b64_e32 v[74:75], v[106:107]
	v_mov_b64_e32 v[76:77], v[108:109]
	v_mov_b64_e32 v[78:79], v[110:111]
	v_mov_b64_e32 v[82:83], v[98:99]
	v_mov_b64_e32 v[84:85], v[100:101]
	v_mov_b64_e32 v[86:87], v[102:103]
	v_mov_b64_e32 v[88:89], v[104:105]
	v_mov_b64_e32 v[90:91], v[106:107]
	v_mov_b64_e32 v[92:93], v[108:109]
	v_mov_b64_e32 v[94:95], v[110:111]
	v_mov_b64_e32 v[34:35], v[98:99]
	v_mov_b64_e32 v[36:37], v[100:101]
	v_mov_b64_e32 v[38:39], v[102:103]
	v_mov_b64_e32 v[40:41], v[104:105]
	v_mov_b64_e32 v[42:43], v[106:107]
	v_mov_b64_e32 v[44:45], v[108:109]
	v_mov_b64_e32 v[46:47], v[110:111]
	v_mov_b64_e32 v[50:51], v[98:99]
	v_mov_b64_e32 v[52:53], v[100:101]
	v_mov_b64_e32 v[54:55], v[102:103]
	v_mov_b64_e32 v[56:57], v[104:105]
	v_mov_b64_e32 v[58:59], v[106:107]
	v_mov_b64_e32 v[60:61], v[108:109]
	v_mov_b64_e32 v[62:63], v[110:111]
	v_mov_b64_e32 v[124:125], v[108:109]
	v_mov_b64_e32 v[122:123], v[106:107]
	v_mov_b64_e32 v[120:121], v[104:105]
	v_mov_b64_e32 v[118:119], v[102:103]
	v_mov_b64_e32 v[116:117], v[100:101]
	v_mov_b64_e32 v[114:115], v[98:99]
	v_mov_b64_e32 v[112:113], v[96:97]
	v_mov_b32_e32 v0, v210
	global_load_lds_dwordx4 v176, s[40:41] nt
	s_mov_b32 m0, s89
	v_lshlrev_b32_e32 v0, 3, v0
	global_load_lds_dwordx4 v190, s[66:67] nt
	s_mov_b32 m0, s91
	v_add_u32_e32 v2, 16, v0
	global_load_lds_dwordx4 v192, s[40:41] nt
	s_mov_b32 m0, s92
	v_or_b32_e32 v1, 1, v0
	global_load_lds_dwordx4 v194, s[66:67] nt
	s_mov_b32 m0, s93
	v_or_b32_e32 v4, 3, v0
	global_load_lds_dwordx4 v176, s[0:1] nt
	s_mov_b32 m0, s94
	v_or_b32_e32 v5, 2, v0
	global_load_lds_dwordx4 v190, s[36:37] nt
	s_mov_b32 m0, s95
	v_or_b32_e32 v6, 5, v0
	global_load_lds_dwordx4 v192, s[0:1] nt
	s_mov_b32 m0, s96
	v_or_b32_e32 v7, 4, v0
	global_load_lds_dwordx4 v194, s[36:37] nt
	s_waitcnt vmcnt(8)
	ds_write_b128 v189, v[144:147]
	ds_write_b128 v189, v[148:151] offset:1024
	ds_write_b128 v189, v[152:155] offset:2048
	ds_write_b128 v189, v[156:159] offset:3072
	ds_write_b128 v189, v[160:163] offset:4096
	ds_write_b128 v189, v[164:167] offset:5120
	ds_write_b128 v189, v[168:171] offset:6144
	ds_write_b128 v189, v[172:175] offset:7168
	v_or_b32_e32 v8, 7, v0
	v_or_b32_e32 v9, 6, v0
	v_add_u32_e32 v3, 17, v0
	v_or_b32_e32 v10, 3, v2
	v_or_b32_e32 v11, 2, v2
	v_or_b32_e32 v12, 5, v2
	v_or_b32_e32 v13, 4, v2
	v_or_b32_e32 v14, 7, v2
	v_or_b32_e32 v15, 6, v2
	v_cvt_f32_i32_e32 v17, v10
	v_cvt_f32_i32_e32 v16, v11
	v_cvt_f32_i32_e32 v11, v12
	v_cvt_f32_i32_e32 v10, v13
	v_cvt_f32_i32_e32 v13, v14
	v_cvt_f32_i32_e32 v12, v15
	v_cvt_f32_i32_e32 v15, v4
	v_cvt_f32_i32_e32 v14, v5
	v_cvt_f32_i32_e32 v5, v6
	v_cvt_f32_i32_e32 v4, v7
	v_cvt_f32_i32_e32 v7, v8
	v_cvt_f32_i32_e32 v6, v9
	v_cvt_f32_i32_e32 v0, v0
	v_cvt_f32_i32_e32 v1, v1
	v_cvt_f32_i32_e32 v3, v3
	v_cvt_f32_i32_e32 v2, v2
	v_pk_mul_f32 v[134:135], v[184:185], v[6:7]
	v_pk_mul_f32 v[132:133], v[184:185], v[4:5]
	v_pk_mul_f32 v[130:131], v[184:185], v[14:15]
	v_pk_mul_f32 v[142:143], v[184:185], v[12:13]
	v_pk_mul_f32 v[140:141], v[184:185], v[10:11]
	v_pk_mul_f32 v[138:139], v[184:185], v[16:17]
	v_pk_mul_f32 v[136:137], v[184:185], v[2:3]
	v_pk_mul_f32 v[128:129], v[186:187], v[0:1]
	v_mov_b64_e32 v[0:1], v[96:97]
	v_mov_b64_e32 v[16:17], v[96:97]
	s_or_b32 s36, s83, 2
	s_or_b32 s37, s83, 1
	v_subrev_u32_e32 v185, s79, v231
	s_add_i32 s66, s79, 0xffffff60
	s_add_i32 s67, s79, 0xffffff40
	s_addk_i32 s79, 0xff20
	s_mov_b32 s40, 0
	s_mov_b32 s41, 0
	v_mov_b64_e32 v[2:3], v[98:99]
	v_mov_b64_e32 v[4:5], v[100:101]
	v_mov_b64_e32 v[6:7], v[102:103]
	v_mov_b64_e32 v[8:9], v[104:105]
	v_mov_b64_e32 v[10:11], v[106:107]
	v_mov_b64_e32 v[12:13], v[108:109]
	v_mov_b64_e32 v[14:15], v[110:111]
	v_mov_b64_e32 v[18:19], v[98:99]
	v_mov_b64_e32 v[20:21], v[100:101]
	v_mov_b64_e32 v[22:23], v[102:103]
	v_mov_b64_e32 v[24:25], v[104:105]
	v_mov_b64_e32 v[26:27], v[106:107]
	v_mov_b64_e32 v[28:29], v[108:109]
	v_mov_b64_e32 v[30:31], v[110:111]
	s_branch .LBB0_754

.LBB0_762:
	s_add_i32 s0, s37, 2
	s_lshl_b32 s0, s0, 17
	s_add_i32 s78, s0, 0xfffc0000
	s_add_u32 s0, s76, s78
	s_addc_u32 s1, s77, 0
	s_add_u32 vcc_lo, s81, s78
	s_addc_u32 vcc_hi, s82, 0
	v_lshl_add_u64 v[144:145], s[0:1], 0, v[176:177]
	s_add_i32 m0, s88, 0x8000
	s_nop 0
	global_load_lds_dwordx4 v[144:145], off nt
	v_lshl_add_u64 v[144:145], vcc, 0, v[190:191]
	s_add_i32 m0, s72, s87
	s_nop 0
	global_load_lds_dwordx4 v[144:145], off nt
	v_lshl_add_u64 v[144:145], s[0:1], 0, v[192:193]
	s_add_i32 m0, s88, 0x8400
	s_nop 0
	global_load_lds_dwordx4 v[144:145], off nt
	v_lshl_add_u64 v[144:145], vcc, 0, v[194:195]
	s_add_i32 m0, s72, s90
	s_nop 0
	global_load_lds_dwordx4 v[144:145], off nt
	s_cmp_ge_i32 s38, s84
	s_cbranch_scc1 .LBB0_758

.LBB0_786:
	s_add_i32 s0, s37, 1
	s_lshl_b32 s0, s0, 17
	s_add_i32 s78, s0, 0xfffc0000
	s_add_u32 s0, s76, s78
	s_addc_u32 s1, s77, 0
	s_add_u32 vcc_lo, s81, s78
	s_mov_b32 m0, s88
	s_addc_u32 vcc_hi, s82, 0
	v_lshl_add_u64 v[144:145], s[0:1], 0, v[176:177]
	global_load_lds_dwordx4 v[144:145], off nt
	v_lshl_add_u64 v[144:145], vcc, 0, v[190:191]
	s_mov_b32 m0, s89
	s_nop 0
	global_load_lds_dwordx4 v[144:145], off nt
	v_lshl_add_u64 v[144:145], s[0:1], 0, v[192:193]
	s_mov_b32 m0, s91
	s_nop 0
	global_load_lds_dwordx4 v[144:145], off nt
	v_lshl_add_u64 v[144:145], vcc, 0, v[194:195]
	s_mov_b32 m0, s92
	s_nop 0
	global_load_lds_dwordx4 v[144:145], off nt
	s_add_i32 s78, s38, -2
	s_cmp_ge_i32 s78, s84
	s_cbranch_scc1 .LBB0_777

.LBB0_799:
	s_lshl_b32 s0, s37, 17
	s_add_i32 s78, s0, 0xfffc0000
	s_add_u32 s0, s76, s78
	s_addc_u32 s1, s77, 0
	s_add_u32 vcc_lo, s81, s78
	s_mov_b32 m0, s93
	s_addc_u32 vcc_hi, s82, 0
	v_lshl_add_u64 v[144:145], s[0:1], 0, v[176:177]
	global_load_lds_dwordx4 v[144:145], off nt
	v_lshl_add_u64 v[144:145], vcc, 0, v[190:191]
	s_mov_b32 m0, s94
	s_nop 0
	global_load_lds_dwordx4 v[144:145], off nt
	v_lshl_add_u64 v[144:145], s[0:1], 0, v[192:193]
	s_mov_b32 m0, s95
	s_nop 0
	global_load_lds_dwordx4 v[144:145], off nt
	v_lshl_add_u64 v[144:145], vcc, 0, v[194:195]
	s_mov_b32 m0, s96
	s_nop 0
	global_load_lds_dwordx4 v[144:145], off nt
	s_add_i32 s78, s38, -4
	s_cmp_ge_i32 s78, s84
	s_cbranch_scc1 .LBB0_783
